# gla_seq: one static s_setprio 1 for waves 4-7 before the chunk loop (section 7.4), on top of EpiDil/P0/P3 changes
# speedup vs baseline: 1.0028x; 1.0028x over previous
; #define LAS __attribute__((address_space(3)))
; __device__ __forceinline__ int tid_local() { int t = threadIdx.x; asm volatile("" : "+v"(t)); return t; }
; __device__ __forceinline__ void gla_seq(CArgs a, LAS unsigned char* lds) {
;     const int blk = blockIdx.x; if (blk >= 128) return;
;     unsigned char* ws = a->ws;
;     const bf16_t* Q = (const bf16_t*)(ws + WS_Q); const bf16_t* Kk = (const bf16_t*)(ws + WS_K); const bf16_t* V = (const bf16_t*)(ws + WS_V);
;     const bf16_t* AIN = (const bf16_t*)(ws + WS_AIN); const float* DEC = (const float*)(ws + WS_DEC); float* ORAW = (float*)(ws + WS_ORAW);
;     const int bh = (blk & 7) + 8 * (blk >> 6), dvs = (blk >> 3) & 7, b = bh >> 2, h = bh & 3;
;     const int tid = tid_local(), lane = tid & 63, wid = __builtin_amdgcn_readfirstlane(tid >> 6), fr = lane & 15, fq = lane >> 4, qq = fr >> 2, pp = lane & 3;
;     constexpr int VB = 64 * VP * 2, SBB = 64 * GP * 2;
;     LAS unsigned char* Vl = lds; LAS unsigned char* Sb = lds + 2 * VB;
;     for (int e = tid; e < SBB / 16; e += 512) *(LAS u32x4*)(Sb + SBB + e * 16) = (u32x4){0, 0, 0, 0};
;     f32x4 S[2][4];
; #pragma unroll
;     for (int r2 = 0; r2 < 2; ++r2)
; #pragma unroll
;         for (int ct = 0; ct < 4; ++ct) S[r2][ct] = (f32x4){0, 0, 0, 0};
;     const int unit0 = bh * 128, vrow = tid >> 3, vch = tid & 7, rt = wid >> 1, ct0 = (wid & 1) * 2;
;     const int dk0 = 16 * (2 * wid) + fr, dk1 = dk0 + 16;
;     const size_t fragoff = (size_t)(lane >> 5) * 1024 + h * 256 + (lane & 31) * 8;
;     const size_t voff = (size_t)vrow * 2048 + h * 512 + dvs * 64 + vch * 8;
;     const int doff = 16 * (2 * wid) + 4 * fq;
;     bf16x8 nq[8], na[2], nk[2][2]; f32x4 nd[2]; u32x4 nv;
;     ...
;     nv = *(const u32x4*)(V + (size_t)(b * SEQ) * 2048 + voff);
;     GLA_LOAD(0);
.LBB0_358:
	s_or_b64 exec, exec, s[12:13]
	s_lshr_b32 s7, s2, 3
	s_and_b32 s6, s2, 7
	s_and_b32 s7, s7, 8
	s_or_b32 s20, s7, s6
	s_ashr_i32 s6, s16, 6
	s_and_b32 s7, s2, 3
	v_ashrrev_i32_e32 v10, 3, v4
	s_lshl_b32 s12, s6, 1
	v_lshlrev_b32_e32 v0, 5, v4
	v_lshlrev_b32_e32 v27, 3, v4
	s_and_b32 s21, s12, 2
	v_and_b32_e32 v0, 0x400, v0
	s_lshl_b32 s12, s7, 8
	v_and_b32_e32 v1, 0xf8, v27
	v_ashrrev_i32_e32 v11, 31, v10
	s_and_b32 s22, s3, 0x1c0
	s_lshl_b32 s3, s20, 11
	v_or3_b32 v6, v0, s12, v1
	v_lshlrev_b64 v[0:1], 11, v[10:11]
	s_lshl_b32 s12, s7, 9
	v_and_b32_e32 v12, 56, v27
	s_and_b32 s3, s3, 0x6000
	v_or3_b32 v0, v0, v12, s12
	s_lshl_b32 s12, s3, 12
	v_or_b32_e32 v0, s22, v0
	s_waitcnt lgkmcnt(0)
	s_add_u32 s14, s10, s12
	s_addc_u32 s15, s11, 0
	v_lshlrev_b64 v[2:3], 1, v[0:1]
	v_lshl_add_u64 v[0:1], s[14:15], 0, v[2:3]
	s_mov_b32 s12, 0x1ba00000
	v_add_co_u32_e32 v14, vcc, s12, v0
	s_ashr_i32 s12, s16, 3
	s_nop 0
	v_addc_co_u32_e32 v15, vcc, 0, v1, vcc
	s_and_b32 s14, s12, -16
	v_lshlrev_b32_e32 v0, 1, v6
	v_mov_b32_e32 v1, 0
	v_lshl_add_u64 v[16:17], s[10:11], 0, v[0:1]
	s_mov_b64 s[18:19], 0x13a00000
	s_ashr_i32 s15, s14, 31
	v_lshl_add_u64 v[18:19], v[16:17], 0, s[18:19]
	s_add_u32 s18, s14, s3
	s_addc_u32 s19, s15, 0
	s_or_b32 s12, s14, 2
	s_lshl_b64 s[18:19], s[18:19], 11
	s_ashr_i32 s17, s12, 31
	v_lshl_add_u64 v[20:21], v[18:19], 0, s[18:19]
	s_add_u32 s18, s12, s3
	s_addc_u32 s19, s17, 0
	s_or_b32 s12, s14, 4
	s_lshl_b64 s[18:19], s[18:19], 11
	s_ashr_i32 s17, s12, 31
	global_load_dwordx4 v[6:9], v[14:15], off
	global_load_dwordx4 v[52:55], v[20:21], off
	v_lshl_add_u64 v[14:15], v[18:19], 0, s[18:19]
	s_add_u32 s18, s12, s3
	s_addc_u32 s19, s17, 0
	s_or_b32 s12, s14, 6
	s_lshl_b64 s[18:19], s[18:19], 11
	s_ashr_i32 s17, s12, 31
	v_lshl_add_u64 v[20:21], v[18:19], 0, s[18:19]
	s_add_u32 s18, s12, s3
	s_addc_u32 s19, s17, 0
	s_or_b32 s12, s14, 8
	s_lshl_b64 s[18:19], s[18:19], 11
	s_ashr_i32 s17, s12, 31
	global_load_dwordx4 v[60:63], v[14:15], off
	global_load_dwordx4 v[56:59], v[20:21], off
	v_lshl_add_u64 v[14:15], v[18:19], 0, s[18:19]
	s_add_u32 s18, s12, s3
	s_addc_u32 s19, s17, 0
	s_or_b32 s12, s14, 10
	s_lshl_b64 s[18:19], s[18:19], 11
	s_ashr_i32 s17, s12, 31
	v_lshl_add_u64 v[20:21], v[18:19], 0, s[18:19]
	s_add_u32 s18, s12, s3
	s_addc_u32 s19, s17, 0
	s_or_b32 s12, s14, 12
	s_lshl_b64 s[18:19], s[18:19], 11
	s_ashr_i32 s17, s12, 31
	global_load_dwordx4 v[72:75], v[14:15], off
	global_load_dwordx4 v[64:67], v[20:21], off
	v_lshl_add_u64 v[14:15], v[18:19], 0, s[18:19]
	s_add_u32 s18, s12, s3
	s_addc_u32 s19, s17, 0
	s_or_b32 s12, s14, 14
	s_lshl_b64 s[18:19], s[18:19], 11
	s_ashr_i32 s17, s12, 31
	v_lshl_add_u64 v[20:21], v[18:19], 0, s[18:19]
	s_add_u32 s18, s12, s3
	s_addc_u32 s19, s17, 0
	s_lshl_b64 s[18:19], s[18:19], 11
	s_lshl_b32 s12, s20, 20
	global_load_dwordx4 v[76:79], v[14:15], off
	global_load_dwordx4 v[68:71], v[20:21], off
	v_lshl_add_u64 v[14:15], v[18:19], 0, s[18:19]
	s_add_u32 s18, s10, s12
	v_and_b32_e32 v5, 63, v4
	s_addc_u32 s19, s11, 0
	s_and_b32 s16, s16, 0x1fffff80
	v_or_b32_e32 v5, s16, v5
	v_lshlrev_b32_e32 v18, 3, v5
	v_ashrrev_i32_e32 v19, 31, v18
	v_lshlrev_b64 v[18:19], 1, v[18:19]
	s_lshl_b32 s16, s6, 3
	v_lshl_add_u64 v[20:21], s[18:19], 0, v[18:19]
	s_mov_b64 s[18:19], 0x300000
	s_mov_b32 s17, 0x300000
	v_lshl_add_u64 v[22:23], v[20:21], 0, s[18:19]
	v_add_co_u32_e32 v20, vcc, s17, v20
	s_ashr_i32 s17, s16, 31
	s_add_u32 s18, s16, s3
	s_mov_b64 s[24:25], 0x17a00000
	s_addc_u32 s19, s17, 0
	v_lshl_add_u64 v[16:17], v[16:17], 0, s[24:25]
	s_lshl_b64 s[18:19], s[18:19], 11
	v_lshl_add_u64 v[24:25], v[16:17], 0, s[18:19]
	s_or_b32 s18, s16, 4
	s_ashr_i32 s19, s18, 31
	s_add_u32 s18, s18, s3
	s_addc_u32 s19, s19, 0
	v_addc_co_u32_e32 v21, vcc, 0, v21, vcc
	s_lshl_b64 s[18:19], s[18:19], 11
	global_load_dwordx4 v[132:135], v[20:21], off
	global_load_dwordx4 v[36:39], v[24:25], off
	v_lshl_add_u64 v[20:21], v[16:17], 0, s[18:19]
	s_or_b32 s18, s16, 2
	s_ashr_i32 s19, s18, 31
	s_add_u32 s18, s18, s3
	s_addc_u32 s19, s19, 0
	s_lshl_b64 s[18:19], s[18:19], 11
	global_load_dwordx4 v[92:95], v[14:15], off
	global_load_dwordx4 v[136:139], v[22:23], off offset:1024
	v_lshl_add_u64 v[14:15], v[16:17], 0, s[18:19]
	s_or_b32 s18, s16, 6
	s_ashr_i32 s19, s18, 31
	s_add_u32 s18, s18, s3
	v_bfe_u32 v13, v4, 4, 2
	s_addc_u32 s19, s19, 0
	v_lshlrev_b32_e32 v11, 2, v13
	s_lshl_b64 s[18:19], s[18:19], 11
	global_load_dwordx4 v[40:43], v[20:21], off
	global_load_dwordx4 v[32:35], v[14:15], off
	v_lshl_add_u64 v[14:15], v[16:17], 0, s[18:19]
	v_lshl_or_b32 v16, s6, 5, v11
	s_lshl_b32 s18, s20, 17
	s_add_u32 s24, s10, s18
	v_ashrrev_i32_e32 v17, 31, v16
	s_addc_u32 s25, s11, 0
	v_lshlrev_b64 v[20:21], 2, v[16:17]
	v_lshl_add_u64 v[22:23], s[24:25], 0, v[20:21]
	s_mov_b64 s[24:25], 0x1300000
	s_mov_b32 s6, 0x1300000
	v_lshl_add_u64 v[24:25], v[22:23], 0, s[24:25]
	v_add_co_u32_e32 v22, vcc, s6, v22
	s_add_i32 s3, s14, s3
	s_nop 0
	v_addc_co_u32_e32 v23, vcc, 0, v23, vcc
	global_load_dwordx4 v[80:83], v[22:23], off
	global_load_dwordx4 v[44:47], v[14:15], off
	global_load_dwordx4 v[48:51], v[24:25], off offset:64
	s_lshl_b32 s7, s7, 11
	s_movk_i32 s23, 0x48
	s_add_u32 s7, s10, s7
	v_mad_u64_u32 v[10:11], s[24:25], v10, s23, v[12:13]
	s_addc_u32 s23, s11, 0
	s_lshl_b32 s22, s22, 2
	s_add_u32 s22, s7, s22
	v_and_b32_e32 v153, 15, v4
	v_bfe_u32 v26, v4, 2, 2
	v_and_b32_e32 v4, 48, v4
	s_addc_u32 s23, s23, 0
	v_mov_b32_e32 v5, v1
	v_lshl_add_u32 v187, v10, 1, 0
	v_add_u32_e32 v184, 0, v4
	v_lshl_add_u64 v[4:5], s[22:23], 0, v[4:5]
	s_mov_b64 s[22:23], 0x2ba00000
	s_mov_b32 s13, 0
	s_waitcnt vmcnt(16)
; #define LAS __attribute__((address_space(3)))
; __device__ __forceinline__ void gla_seq(CArgs a, LAS unsigned char* lds) {
;     ...
;     for (int e = tid; e < SBB / 16; e += 512) *(LAS u32x4*)(Sb + SBB + e * 16) = (u32x4){0, 0, 0, 0};
;     f32x4 S[2][4];
; #pragma unroll
;     for (int r2 = 0; r2 < 2; ++r2)
; #pragma unroll
;         for (int ct = 0; ct < 4; ++ct) S[r2][ct] = (f32x4){0, 0, 0, 0};
;     const int unit0 = bh * 128, vrow = tid >> 3, vch = tid & 7, rt = wid >> 1, ct0 = (wid & 1) * 2;
;     const int dk0 = 16 * (2 * wid) + fr, dk1 = dk0 + 16;
;     const size_t fragoff = (size_t)(lane >> 5) * 1024 + h * 256 + (lane & 31) * 8;
;     const size_t voff = (size_t)vrow * 2048 + h * 512 + dvs * 64 + vch * 8;
;     const int doff = 16 * (2 * wid) + 4 * fq;
;     bf16x8 nq[8], na[2], nk[2][2]; f32x4 nd[2]; u32x4 nv;
;     ...
;     nv = *(const u32x4*)(V + (size_t)(b * SEQ) * 2048 + voff);
;     GLA_LOAD(0);
;     *(LAS u32x4*)(Vl + (vrow * VP + vch * 8) * 2) = nv;
;     __syncthreads();
;     for (int c = 0; c < 128; ++c) {
;         const int pb = c & 1;
;         bf16x8 cq[8], ca[2], ck[2][2]; f32x4 cd[2];
; #pragma unroll
;         for (int kk = 0; kk < 8; ++kk) cq[kk] = nq[kk];
; #pragma unroll
;         for (int kk = 0; kk < 2; ++kk) { ca[kk] = na[kk]; ck[0][kk] = nk[0][kk]; ck[1][kk] = nk[1][kk]; }
;         cd[0] = nd[0]; cd[1] = nd[1];
;         if (c + 1 < 128) { nv = *(const u32x4*)(V + (size_t)(b * SEQ + (c + 1) * 64) * 2048 + voff); GLA_LOAD(c + 1); }
;         const LAS unsigned char* Vc = Vl + pb * VB; const LAS unsigned char* Sp = Sb + (pb ^ 1) * SBB;
	ds_write_b128 v187, v[6:9]
	v_lshl_add_u64 v[164:165], v[4:5], 0, s[22:23]
	s_lshl_b32 s24, s21, 5
	s_or_b32 s22, s21, 1
	s_lshl_b32 s25, s21, 4
	s_movk_i32 s21, 0x108
	v_mov_b32_e32 v7, 0x1080
	v_mov_b32_e32 v8, 0x2100
	v_mov_b32_e32 v9, 0x3180
	s_bfe_u32 s23, s20, 0x130002
	v_mad_u32_u24 v7, v153, s21, v7
	v_mad_u32_u24 v8, v153, s21, v8
	v_mad_u32_u24 v9, v153, s21, v9
	s_lshl_b32 s20, s23, 25
	s_mov_b32 s21, s13
	v_lshl_add_u64 v[2:3], s[20:21], 0, v[2:3]
	s_mov_b64 s[20:21], 0x1ba40000
	s_lshl_b32 s7, s22, 5
	s_lshl_b32 s22, s22, 4
	v_lshl_add_u64 v[168:169], v[2:3], 0, s[20:21]
	s_lshl_b32 s20, s23, 24
	s_lshl_b64 s[14:15], s[14:15], 11
	s_add_u32 s14, s20, s14
	s_addc_u32 s15, 0, s15
	v_or_b32_e32 v5, s25, v153
	v_or_b32_e32 v170, s14, v0
	v_mov_b32_e32 v171, s15
	s_lshl_b64 s[14:15], s[16:17], 11
	v_lshl_or_b32 v4, v13, 3, v26
	v_mul_u32_u24_e32 v186, 0x210, v5
	v_or_b32_e32 v5, s22, v153
	s_add_u32 s14, s20, s14
	s_mov_b32 s19, s13
	v_and_b32_e32 v6, 24, v27
	v_mul_u32_u24_e32 v4, 0x90, v4
	v_mul_u32_u24_e32 v185, 0x210, v5
	v_mul_u32_u24_e32 v5, 0x108, v153
	v_or_b32_e32 v10, 16, v16
	s_addc_u32 s15, 0, s15
	v_add_lshl_u32 v182, v16, v5, 1
	v_add_lshl_u32 v181, v16, v7, 1
	v_add_lshl_u32 v180, v16, v8, 1
	v_add_lshl_u32 v179, v16, v9, 1
	v_add_lshl_u32 v178, v10, v5, 1
	v_add_lshl_u32 v163, v10, v7, 1
	v_add_lshl_u32 v159, v10, v8, 1
	v_add_lshl_u32 v155, v10, v9, 1
	v_add3_u32 v183, 0, v6, v4
	v_or_b32_e32 v166, s3, v153
	v_or_b32_e32 v172, s14, v0
	v_mov_b32_e32 v173, s15
	v_lshl_add_u64 v[174:175], s[12:13], 0, v[18:19]
	v_lshl_add_u64 v[176:177], s[18:19], 0, v[20:21]
	s_mov_b32 s26, 0x13a21000
	s_mov_b32 s27, 0x13a23000
	s_mov_b32 s28, 0x13a25000
	s_mov_b32 s29, 0x13a27000
	s_mov_b32 s31, 0x302000
	s_mov_b32 s33, 0x17a21000
	s_mov_b32 s35, 0x17a23000
	s_lshl_b32 s14, s22, 2
	s_mov_b64 s[16:17], 0x40000
	s_mov_b64 s[18:19], 0x20000
	s_mov_b64 s[20:21], 0x2000
	s_mov_b64 s[22:23], 0x400
	s_mov_b32 s36, 0
	v_mov_b32_e32 v0, v1
	v_mov_b32_e32 v2, v1
	v_mov_b32_e32 v3, v1
	v_mov_b32_e32 v4, v1
	v_mov_b32_e32 v5, v1
	v_mov_b32_e32 v6, v1
	v_mov_b32_e32 v7, v1
	v_mov_b32_e32 v8, v1
	v_mov_b32_e32 v9, v1
	v_mov_b32_e32 v10, v1
	v_mov_b32_e32 v11, v1
	v_mov_b32_e32 v12, v1
	v_mov_b32_e32 v13, v1
	v_mov_b32_e32 v14, v1
	v_mov_b32_e32 v15, v1
	v_mov_b32_e32 v16, v1
	v_mov_b32_e32 v17, v1
	v_mov_b32_e32 v18, v1
	v_mov_b32_e32 v19, v1
	v_mov_b32_e32 v20, v1
	v_mov_b32_e32 v21, v1
	v_mov_b32_e32 v22, v1
	v_mov_b32_e32 v23, v1
	v_mov_b32_e32 v24, v1
	v_mov_b32_e32 v25, v1
	v_mov_b32_e32 v26, v1
	v_mov_b32_e32 v27, v1
	v_mov_b32_e32 v28, v1
	v_mov_b32_e32 v29, v1
	v_mov_b32_e32 v30, v1
	v_mov_b32_e32 v31, v1
	s_waitcnt lgkmcnt(0)
	s_barrier
	v_readfirstlane_b32 s98, v154
	s_lshr_b32 s98, s98, 6
	s_cmp_ge_u32 s98, 4
	s_cbranch_scc0 .Lgla_prio_done
	s_setprio 1
.Lgla_prio_done:
.LBB0_359:
	s_waitcnt vmcnt(1)
	v_mov_b64_e32 v[130:131], v[46:47]
	v_mov_b64_e32 v[128:129], v[44:45]
	v_mov_b64_e32 v[110:111], v[58:59]
	v_lshl_add_u64 v[44:45], s[10:11], 0, v[170:171]
	v_mov_b64_e32 v[108:109], v[56:57]
	v_add_co_u32_e32 v58, vcc, s26, v44
	v_mov_b64_e32 v[90:91], v[70:71]
	s_nop 0
	v_addc_co_u32_e32 v59, vcc, 0, v45, vcc
	v_mov_b64_e32 v[88:89], v[68:69]
	v_add_co_u32_e32 v68, vcc, s27, v44
	v_mov_b64_e32 v[84:85], v[92:93]
	s_nop 0
	v_addc_co_u32_e32 v69, vcc, 0, v45, vcc
	v_add_co_u32_e32 v70, vcc, s28, v44
	v_mov_b64_e32 v[118:119], v[54:55]
	s_nop 0
	v_addc_co_u32_e32 v71, vcc, 0, v45, vcc
	v_mov_b64_e32 v[86:87], v[94:95]
	v_add_co_u32_e32 v92, vcc, s29, v44
	v_mov_b64_e32 v[120:121], v[136:137]
	v_mov_b64_e32 v[116:117], v[52:53]
	v_lshl_add_u64 v[52:53], s[10:11], 0, v[174:175]
	v_addc_co_u32_e32 v93, vcc, 0, v45, vcc
	v_mov_b64_e32 v[122:123], v[138:139]
	v_add_co_u32_e32 v136, vcc, s31, v52
	s_and_b32 s37, s36, 1
	v_lshl_add_u64 v[54:55], s[10:11], 0, v[172:173]
	v_addc_co_u32_e32 v137, vcc, 0, v53, vcc
	v_ashrrev_i32_e32 v167, 31, v166
	v_add_co_u32_e32 v144, vcc, s33, v54
	s_mul_i32 s38, s37, 0x2400
	v_mov_b64_e32 v[102:103], v[66:67]
	v_lshl_add_u64 v[46:47], s[10:11], 0, v[168:169]
	v_addc_co_u32_e32 v145, vcc, 0, v55, vcc
	v_lshlrev_b64 v[204:205], 13, v[166:167]
	v_add_u32_e32 v167, s38, v183
	v_mov_b64_e32 v[100:101], v[64:65]
	global_load_dwordx4 v[188:191], v[46:47], off
	v_add_co_u32_e32 v200, vcc, s35, v54
	v_pk_mul_f32 v[30:31], v[30:31], v[82:83]
	v_pk_mul_f32 v[28:29], v[28:29], v[80:81]
	v_pk_mul_f32 v[26:27], v[26:27], v[82:83]
	v_pk_mul_f32 v[24:25], v[24:25], v[80:81]
	v_pk_mul_f32 v[22:23], v[22:23], v[82:83]
	v_pk_mul_f32 v[20:21], v[20:21], v[80:81]
	v_pk_mul_f32 v[18:19], v[18:19], v[82:83]
	v_pk_mul_f32 v[16:17], v[16:17], v[80:81]
	ds_read_b64_tr_b16 v[46:47], v167 offset:576
	ds_read_b64_tr_b16 v[44:45], v167
	ds_read_b64_tr_b16 v[64:65], v167 offset:32
	ds_read_b64_tr_b16 v[80:81], v167 offset:64
	ds_read_b64_tr_b16 v[140:141], v167 offset:96
	ds_read_b64_tr_b16 v[66:67], v167 offset:608
	ds_read_b64_tr_b16 v[82:83], v167 offset:640
	ds_read_b64_tr_b16 v[142:143], v167 offset:672
	v_lshl_add_u64 v[56:57], s[10:11], 0, v[176:177]
	v_addc_co_u32_e32 v201, vcc, 0, v55, vcc
	v_mov_b64_e32 v[124:125], v[132:133]
	v_mov_b64_e32 v[114:115], v[62:63]
	v_mov_b64_e32 v[106:107], v[74:75]
	v_mov_b64_e32 v[98:99], v[78:79]
	v_add_co_u32_e32 v202, vcc, s6, v56
	s_waitcnt vmcnt(1)
	v_pk_mul_f32 v[10:11], v[10:11], v[50:51]
	v_pk_mul_f32 v[8:9], v[8:9], v[48:49]
	v_mov_b64_e32 v[126:127], v[134:135]
	v_mov_b64_e32 v[112:113], v[60:61]
	v_mov_b64_e32 v[104:105], v[72:73]
	v_mov_b64_e32 v[96:97], v[76:77]
	v_addc_co_u32_e32 v203, vcc, 0, v57, vcc
	v_pk_mul_f32 v[14:15], v[14:15], v[50:51]
	v_pk_mul_f32 v[12:13], v[12:13], v[48:49]
	v_pk_mul_f32 v[6:7], v[6:7], v[50:51]
	v_pk_mul_f32 v[4:5], v[4:5], v[48:49]
	v_pk_mul_f32 v[2:3], v[2:3], v[50:51]
	v_pk_mul_f32 v[0:1], v[0:1], v[48:49]
	global_load_dwordx4 v[52:55], v[58:59], off offset:-4096
	s_waitcnt lgkmcnt(2)
; #define LAS __attribute__((address_space(3)))
; __device__ __forceinline__ s16x4 tr4(const LAS unsigned char* p) { return __builtin_bit_cast(s16x4, __builtin_amdgcn_ds_read_tr16_b64_v4i16((LAS s16x4*)p)); }
; __device__ __forceinline__ bf16x8 cat8(s16x4 a, s16x4 b) { return (bf16x8){a[0], a[1], a[2], a[3], b[0], b[1], b[2], b[3]}; }
; #define MFMA16(a, b, c) __builtin_amdgcn_mfma_f32_16x16x32_bf16((a), (b), (c), 0, 0, 0)
; __device__ __forceinline__ void gla_seq(CArgs a, LAS unsigned char* lds) {
;     ...
;         const LAS unsigned char* Vc = Vl + pb * VB; const LAS unsigned char* Sp = Sb + (pb ^ 1) * SBB;
;         {
;             f32x4 o[2] = {{0, 0, 0, 0}, {0, 0, 0, 0}};
; #pragma unroll
;             for (int kk = 0; kk < 2; ++kk)
; #pragma unroll
;                 for (int c2 = 0; c2 < 2; ++c2) {
;                     const LAS unsigned char* vp = Vc + ((32 * kk + 8 * fq + qq) * VP + 16 * (ct0 + c2) + 4 * pp) * 2;
;                     o[c2] = MFMA16(cat8(tr4(vp), tr4(vp + 4 * VP * 2)), ca[kk], o[c2]);
;                 }
; #pragma unroll
;             for (int kk = 0; kk < 8; ++kk)
; #pragma unroll
;                 for (int c2 = 0; c2 < 2; ++c2) {
;                     const bf16x8 bfr = *(const LAS bf16x8*)(Sp + ((16 * (ct0 + c2) + fr) * GP + 32 * kk + 8 * fq) * 2);
;                     o[c2] = MFMA16(bfr, cq[kk], o[c2]);
;                 }
;             const int t0 = b * SEQ + c * 64;
; #pragma unroll
;             for (int c2 = 0; c2 < 2; ++c2)
;                 *(f32x4*)(ORAW + (size_t)(t0 + 16 * rt + fr) * 2048 + h * 512 + dvs * 64 + 16 * (ct0 + c2) + 4 * fq) = o[c2];
;         }
;         {
; #pragma unroll
;             for (int r2 = 0; r2 < 2; ++r2)
; #pragma unroll
;                 for (int ct = 0; ct < 4; ++ct) S[r2][ct] = S[r2][ct] * cd[r2];
; #pragma unroll
;             for (int kk = 0; kk < 2; ++kk)
; #pragma unroll
;                 for (int ct = 0; ct < 4; ++ct) {
;                     const LAS unsigned char* vp = Vc + ((32 * kk + 8 * fq + qq) * VP + 16 * ct + 4 * pp) * 2;
;                     const bf16x8 bfr = cat8(tr4(vp), tr4(vp + 4 * VP * 2));
; #pragma unroll
;                     for (int r2 = 0; r2 < 2; ++r2) S[r2][ct] = MFMA16(ck[r2][kk], bfr, S[r2][ct]);
;                 }
;         }
	v_mfma_f32_16x16x32_bf16 v[24:27], v[36:39], v[64:67], v[24:27]
	global_load_dwordx4 v[60:63], v[58:59], off
	s_nop 0
	global_load_dwordx4 v[56:59], v[68:69], off offset:-4096
	global_load_dwordx4 v[72:75], v[68:69], off
	s_lshl_b32 s12, s25, 2
	s_mov_b32 s15, s13
	v_mfma_f32_16x16x32_bf16 v[8:11], v[40:43], v[64:67], v[8:11]
	global_load_dwordx4 v[64:67], v[70:71], off offset:-4096
	global_load_dwordx4 v[76:79], v[70:71], off
	s_nop 0
	global_load_dwordx4 v[68:71], v[92:93], off offset:-4096
	s_nop 0
	global_load_dwordx4 v[92:95], v[92:93], off
	s_nop 0
	global_load_dwordx4 v[132:135], v[136:137], off
	global_load_dwordx4 v[148:151], v[144:145], off offset:-4096
	s_xor_b32 s39, s37, 1
	global_load_dwordx4 v[136:139], v[136:137], off offset:1024
	ds_read_b64_tr_b16 v[48:49], v167 offset:4608
	ds_read_b64_tr_b16 v[50:51], v167 offset:5184
	v_mfma_f32_16x16x32_bf16 v[28:31], v[36:39], v[44:47], v[28:31]
	s_mul_i32 s38, s39, 0x8400
	s_mul_i32 s37, s37, 0x8400
	s_add_i32 s37, s37, 0
	v_mfma_f32_16x16x32_bf16 v[12:15], v[40:43], v[44:47], v[12:15]
	s_add_i32 s36, s36, 1
	s_mulk_i32 s39, 0x2400
	v_add_u32_e32 v207, s37, v180
	s_waitcnt lgkmcnt(3)
	v_mfma_f32_16x16x32_bf16 v[20:23], v[36:39], v[80:83], v[20:23]
	v_add_u32_e32 v209, s37, v163
	v_lshl_add_u64 v[168:169], v[168:169], 0, s[16:17]
	v_lshl_add_u64 v[170:171], v[170:171], 0, s[18:19]
	v_mfma_f32_16x16x32_bf16 v[4:7], v[40:43], v[80:83], v[4:7]
	v_lshl_add_u64 v[172:173], v[172:173], 0, s[18:19]
	v_lshl_add_u64 v[174:175], v[174:175], 0, s[20:21]
	v_lshl_add_u64 v[176:177], v[176:177], 0, s[22:23]
	s_waitcnt lgkmcnt(2)
	v_mfma_f32_16x16x32_bf16 v[16:19], v[36:39], v[140:143], v[16:19]
	ds_read_b64_tr_b16 v[36:37], v167 offset:4640
	ds_read_b64_tr_b16 v[192:193], v167 offset:4672
	ds_read_b64_tr_b16 v[196:197], v167 offset:4704
	ds_read_b64_tr_b16 v[38:39], v167 offset:5216
	ds_read_b64_tr_b16 v[194:195], v167 offset:5248
	ds_read_b64_tr_b16 v[198:199], v167 offset:5280
	v_add_u32_e32 v166, 64, v166
	v_mfma_f32_16x16x32_bf16 v[0:3], v[40:43], v[140:143], v[0:3]
	global_load_dwordx4 v[144:147], v[144:145], off
	s_nop 0
	global_load_dwordx4 v[140:143], v[200:201], off offset:-4096
	global_load_dwordx4 v[44:47], v[200:201], off
	v_add_u32_e32 v42, s24, v167
	v_lshl_add_u64 v[40:41], v[164:165], 0, v[204:205]
	s_waitcnt lgkmcnt(6)
	v_mfma_f32_16x16x32_bf16 v[28:31], v[32:35], v[48:51], v[28:31]
	v_add_u32_e32 v167, s7, v167
	v_lshl_add_u64 v[200:201], v[40:41], 0, s[12:13]
	v_add_u32_e32 v204, s38, v184
	v_mfma_f32_16x16x32_bf16 v[12:15], v[128:131], v[48:51], v[12:15]
	global_load_dwordx4 v[80:83], v[202:203], off offset:1024
	global_load_dwordx4 v[48:51], v[202:203], off offset:1088
	v_lshl_add_u64 v[202:203], v[40:41], 0, s[14:15]
	v_add_u32_e32 v205, s37, v182
	s_waitcnt lgkmcnt(2)
	v_mfma_f32_16x16x32_bf16 v[24:27], v[32:35], v[36:39], v[24:27]
	v_add_u32_e32 v206, s37, v181
	v_add_u32_e32 v208, s37, v178
	v_add_u32_e32 v210, s37, v159
	v_mfma_f32_16x16x32_bf16 v[8:11], v[128:131], v[36:39], v[8:11]
	ds_read_b64_tr_b16 v[36:37], v42
	ds_read_b64_tr_b16 v[38:39], v42 offset:576
	v_add_u32_e32 v211, s39, v187
	s_waitcnt lgkmcnt(3)
	v_mfma_f32_16x16x32_bf16 v[20:23], v[32:35], v[192:195], v[20:23]
	s_cmpk_eq_i32 s36, 0x7f
	v_mfma_f32_16x16x32_bf16 v[4:7], v[128:131], v[192:195], v[4:7]
	v_add_u32_e32 v192, v204, v186
	s_waitcnt lgkmcnt(2)
	v_mfma_f32_16x16x32_bf16 v[16:19], v[32:35], v[196:199], v[16:19]
	ds_read_b64_tr_b16 v[32:33], v167
	ds_read_b64_tr_b16 v[40:41], v42 offset:4608
	ds_read_b64_tr_b16 v[42:43], v42 offset:5184
	v_mfma_f32_16x16x32_bf16 v[0:3], v[128:131], v[196:199], v[0:3]
	ds_read_b64_tr_b16 v[34:35], v167 offset:576
	ds_read_b64_tr_b16 v[128:129], v167 offset:4608
	ds_read_b64_tr_b16 v[130:131], v167 offset:5184
	v_add_u32_e32 v196, v204, v185
	v_add_u32_e32 v167, s37, v179
	s_waitcnt lgkmcnt(6)
	v_mfma_f32_16x16x32_bf16 v[36:39], v[36:39], v[124:127], 0
	v_add_u32_e32 v204, s37, v155
	s_waitcnt lgkmcnt(2)
	v_mfma_f32_16x16x32_bf16 v[32:35], v[32:35], v[124:127], 0
	v_mfma_f32_16x16x32_bf16 v[36:39], v[40:43], v[120:123], v[36:39]
	s_waitcnt lgkmcnt(0)
	v_mfma_f32_16x16x32_bf16 v[32:35], v[128:131], v[120:123], v[32:35]
	ds_read_b128 v[40:43], v192 offset:18432
	ds_read_b128 v[120:123], v192 offset:18496
	s_waitcnt lgkmcnt(1)
	v_mfma_f32_16x16x32_bf16 v[36:39], v[40:43], v[116:119], v[36:39]
	ds_read_b128 v[40:43], v196 offset:18432
	ds_read_b128 v[124:127], v196 offset:18496
	s_waitcnt lgkmcnt(1)
	v_mfma_f32_16x16x32_bf16 v[32:35], v[40:43], v[116:119], v[32:35]
	ds_read_b128 v[40:43], v192 offset:18560
	v_mfma_f32_16x16x32_bf16 v[36:39], v[120:123], v[112:115], v[36:39]
	s_waitcnt lgkmcnt(1)
	v_mfma_f32_16x16x32_bf16 v[32:35], v[124:127], v[112:115], v[32:35]
	ds_read_b128 v[112:115], v196 offset:18560
	ds_read_b128 v[116:119], v192 offset:18624
	s_waitcnt lgkmcnt(2)
	v_mfma_f32_16x16x32_bf16 v[36:39], v[40:43], v[108:111], v[36:39]
	ds_read_b128 v[40:43], v196 offset:18624
	ds_read_b128 v[120:123], v192 offset:18688
	ds_read_b128 v[124:127], v192 offset:18752
	s_waitcnt lgkmcnt(4)
	v_mfma_f32_16x16x32_bf16 v[32:35], v[112:115], v[108:111], v[32:35]
	ds_read_b128 v[108:111], v196 offset:18688
	ds_read_b128 v[112:115], v196 offset:18752
	ds_read_b128 v[128:131], v192 offset:18816
	s_waitcnt lgkmcnt(6)
	v_mfma_f32_16x16x32_bf16 v[36:39], v[116:119], v[104:107], v[36:39]
	ds_read_b128 v[116:119], v192 offset:18880
	ds_read_b128 v[192:195], v196 offset:18816
	ds_read_b128 v[196:199], v196 offset:18880
	s_waitcnt lgkmcnt(8)
	v_mfma_f32_16x16x32_bf16 v[32:35], v[40:43], v[104:107], v[32:35]
	v_cvt_pk_bf16_f32 v40, v28, v29
	v_cvt_pk_bf16_f32 v41, v30, v31
	v_cvt_pk_bf16_f32 v42, v24, v25
	s_waitcnt lgkmcnt(7)
; #define LAS __attribute__((address_space(3)))
; __device__ __forceinline__ unsigned pk2(float lo, float hi) { return pg8::cvt_pk_bf16(lo, hi); }
; __device__ __forceinline__ s16x4 tr4(const LAS unsigned char* p) { return __builtin_bit_cast(s16x4, __builtin_amdgcn_ds_read_tr16_b64_v4i16((LAS s16x4*)p)); }
; __device__ __forceinline__ bf16x8 cat8(s16x4 a, s16x4 b) { return (bf16x8){a[0], a[1], a[2], a[3], b[0], b[1], b[2], b[3]}; }
; #define MFMA16(a, b, c) __builtin_amdgcn_mfma_f32_16x16x32_bf16((a), (b), (c), 0, 0, 0)
; __device__ __forceinline__ void gla_seq(CArgs a, LAS unsigned char* lds) {
;     ...
;         {
;             f32x4 o[2] = {{0, 0, 0, 0}, {0, 0, 0, 0}};
; #pragma unroll
;             for (int kk = 0; kk < 2; ++kk)
; #pragma unroll
;                 for (int c2 = 0; c2 < 2; ++c2) {
;                     const LAS unsigned char* vp = Vc + ((32 * kk + 8 * fq + qq) * VP + 16 * (ct0 + c2) + 4 * pp) * 2;
;                     o[c2] = MFMA16(cat8(tr4(vp), tr4(vp + 4 * VP * 2)), ca[kk], o[c2]);
;                 }
; #pragma unroll
;             for (int kk = 0; kk < 8; ++kk)
; #pragma unroll
;                 for (int c2 = 0; c2 < 2; ++c2) {
;                     const bf16x8 bfr = *(const LAS bf16x8*)(Sp + ((16 * (ct0 + c2) + fr) * GP + 32 * kk + 8 * fq) * 2);
;                     o[c2] = MFMA16(bfr, cq[kk], o[c2]);
;                 }
;             const int t0 = b * SEQ + c * 64;
; #pragma unroll
;             for (int c2 = 0; c2 < 2; ++c2)
;                 *(f32x4*)(ORAW + (size_t)(t0 + 16 * rt + fr) * 2048 + h * 512 + dvs * 64 + 16 * (ct0 + c2) + 4 * fq) = o[c2];
;     ...
;         LAS unsigned char* Sn = Sb + pb * SBB;
; #pragma unroll
;         for (int r2 = 0; r2 < 2; ++r2)
; #pragma unroll
;             for (int ct = 0; ct < 4; ++ct) {
;                 u32x2 w; w.x = pk2(S[r2][ct][0], S[r2][ct][1]); w.y = pk2(S[r2][ct][2], S[r2][ct][3]);
;                 *(LAS u32x2*)(Sn + ((16 * ct + fr) * GP + 16 * (2 * wid + r2) + 4 * fq) * 2) = w;
;             }
;         if (c + 1 < 128) *(LAS u32x4*)(Vl + (pb ^ 1) * VB + (vrow * VP + vch * 8) * 2) = nv;
;         __syncthreads();
	v_mfma_f32_16x16x32_bf16 v[36:39], v[120:123], v[100:103], v[36:39]
	v_cvt_pk_bf16_f32 v43, v26, v27
	v_cvt_pk_bf16_f32 v104, v20, v21
	v_cvt_pk_bf16_f32 v105, v22, v23
	s_waitcnt lgkmcnt(5)
	v_mfma_f32_16x16x32_bf16 v[32:35], v[108:111], v[100:103], v[32:35]
	v_cvt_pk_bf16_f32 v106, v8, v9
	v_cvt_pk_bf16_f32 v107, v10, v11
	v_cvt_pk_bf16_f32 v100, v16, v17
	v_mfma_f32_16x16x32_bf16 v[36:39], v[124:127], v[96:99], v[36:39]
	v_cvt_pk_bf16_f32 v101, v18, v19
	v_cvt_pk_bf16_f32 v102, v12, v13
	v_cvt_pk_bf16_f32 v103, v14, v15
	s_waitcnt lgkmcnt(4)
	v_mfma_f32_16x16x32_bf16 v[32:35], v[112:115], v[96:99], v[32:35]
	v_cvt_pk_bf16_f32 v96, v4, v5
	v_cvt_pk_bf16_f32 v97, v6, v7
	v_cvt_pk_bf16_f32 v98, v0, v1
	s_waitcnt lgkmcnt(3)
	v_mfma_f32_16x16x32_bf16 v[36:39], v[128:131], v[88:91], v[36:39]
	v_cvt_pk_bf16_f32 v99, v2, v3
	ds_write_b64 v205, v[40:41] offset:18432
	ds_write_b64 v206, v[42:43] offset:18432
	ds_write_b64 v207, v[104:105] offset:18432
	ds_write_b64 v167, v[100:101] offset:18432
	ds_write_b64 v208, v[102:103] offset:18432
	s_waitcnt lgkmcnt(6)
	v_mfma_f32_16x16x32_bf16 v[32:35], v[192:195], v[88:91], v[32:35]
	ds_write_b64 v209, v[106:107] offset:18432
	ds_write_b64 v210, v[96:97] offset:18432
	ds_write_b64 v204, v[98:99] offset:18432
	s_waitcnt vmcnt(3)
	v_mov_b32_e32 v40, v140
	v_mov_b32_e32 v41, v141
	v_mfma_f32_16x16x32_bf16 v[36:39], v[116:119], v[84:87], v[36:39]
	v_mov_b32_e32 v42, v142
	v_mov_b32_e32 v43, v143
	s_waitcnt lgkmcnt(8)
	v_mfma_f32_16x16x32_bf16 v[32:35], v[196:199], v[84:87], v[32:35]
	s_nop 3
	global_store_dwordx4 v[200:201], v[36:39], off
	s_nop 2
	global_store_dwordx4 v[202:203], v[32:35], off
	v_mov_b32_e32 v36, v148
	v_mov_b32_e32 v37, v149
	v_mov_b32_e32 v38, v150
	v_mov_b32_e32 v39, v151
	v_mov_b32_e32 v32, v144
	v_mov_b32_e32 v33, v145
	v_mov_b32_e32 v34, v146
	v_mov_b32_e32 v35, v147
	ds_write_b128 v211, v[188:191]
	s_waitcnt lgkmcnt(0)
	s_barrier
	s_cbranch_scc0 .LBB0_359
	v_add_u32_e32 v38, s24, v183
	ds_read_b64_tr_b16 v[32:33], v38 offset:9216
	ds_read_b64_tr_b16 v[34:35], v38 offset:9792
	v_add_u32_e32 v86, s7, v183
	ds_read_b64_tr_b16 v[36:37], v38 offset:13824
	ds_read_b64_tr_b16 v[38:39], v38 offset:14400
	ds_read_b64_tr_b16 v[40:41], v86 offset:9216
	ds_read_b64_tr_b16 v[42:43], v86 offset:9792
	ds_read_b64_tr_b16 v[84:85], v86 offset:13824
	ds_read_b64_tr_b16 v[86:87], v86 offset:14400
	s_waitcnt lgkmcnt(2)
	v_mfma_f32_16x16x32_bf16 v[40:43], v[40:43], v[132:135], 0
	v_add_u32_e32 v88, v184, v186
	s_mov_b64 s[6:7], 0x3f80000
	s_mov_b32 s13, 0
	v_mfma_f32_16x16x32_bf16 v[32:35], v[32:35], v[132:135], 0
	s_mov_b32 s15, s13
	s_waitcnt vmcnt(3)
	v_pk_mul_f32 v[30:31], v[82:83], v[30:31]
	v_pk_mul_f32 v[28:29], v[80:81], v[28:29]
	v_mfma_f32_16x16x32_bf16 v[32:35], v[36:39], v[136:139], v[32:35]
	v_mul_f32_e64 v26, v82, v26
	v_mul_f32_e64 v27, v83, v27
	v_pk_mul_f32 v[24:25], v[80:81], v[24:25]
	s_waitcnt vmcnt(2)
	v_pk_mul_f32 v[14:15], v[50:51], v[14:15]
	s_waitcnt lgkmcnt(0)
	v_mfma_f32_16x16x32_bf16 v[36:39], v[84:87], v[136:139], v[40:43]
	v_add_u32_e32 v84, v184, v185
	v_pk_mul_f32 v[12:13], v[48:49], v[12:13]
	v_pk_mul_f32 v[10:11], v[50:51], v[10:11]
	ds_read_b128 v[40:43], v88 offset:18432
	s_waitcnt lgkmcnt(0)
	v_mfma_f32_16x16x32_bf16 v[32:35], v[40:43], v[52:55], v[32:35]
	ds_read_b128 v[40:43], v84 offset:18432
	v_pk_mul_f32 v[8:9], v[48:49], v[8:9]
	v_pk_mul_f32 v[22:23], v[82:83], v[22:23]
	s_waitcnt lgkmcnt(0)
	v_mfma_f32_16x16x32_bf16 v[36:39], v[40:43], v[52:55], v[36:39]
	ds_read_b128 v[40:43], v88 offset:18496
	v_pk_mul_f32 v[20:21], v[80:81], v[20:21]
	v_pk_mul_f32 v[18:19], v[82:83], v[18:19]
	s_waitcnt lgkmcnt(0)
	v_mfma_f32_16x16x32_bf16 v[32:35], v[40:43], v[60:63], v[32:35]
	ds_read_b128 v[40:43], v84 offset:18496
	v_pk_mul_f32 v[16:17], v[80:81], v[16:17]
	v_pk_mul_f32 v[6:7], v[50:51], v[6:7]
	s_waitcnt lgkmcnt(0)
	v_mfma_f32_16x16x32_bf16 v[36:39], v[40:43], v[60:63], v[36:39]
	ds_read_b128 v[40:43], v88 offset:18560
	ds_read_b128 v[52:55], v88 offset:18624
	v_pk_mul_f32 v[4:5], v[48:49], v[4:5]
	v_pk_mul_f32 v[2:3], v[50:51], v[2:3]
	s_waitcnt lgkmcnt(1)
	v_mfma_f32_16x16x32_bf16 v[32:35], v[40:43], v[56:59], v[32:35]
	ds_read_b128 v[40:43], v84 offset:18560
	ds_read_b128 v[60:63], v84 offset:18624
	v_pk_mul_f32 v[0:1], v[48:49], v[0:1]
	s_waitcnt lgkmcnt(1)
	v_mfma_f32_16x16x32_bf16 v[36:39], v[40:43], v[56:59], v[36:39]
	v_mfma_f32_16x16x32_bf16 v[32:35], v[52:55], v[72:75], v[32:35]
	ds_read_b128 v[40:43], v88 offset:18688
	ds_read_b128 v[52:55], v88 offset:18752
	s_waitcnt lgkmcnt(2)
	v_mfma_f32_16x16x32_bf16 v[36:39], v[60:63], v[72:75], v[36:39]
	s_waitcnt lgkmcnt(1)
	v_mfma_f32_16x16x32_bf16 v[32:35], v[40:43], v[64:67], v[32:35]
	ds_read_b128 v[40:43], v84 offset:18688
	ds_read_b128 v[56:59], v84 offset:18752
	s_waitcnt lgkmcnt(1)
; #define LAS __attribute__((address_space(3)))
; __device__ __forceinline__ void gla_seq(CArgs a, LAS unsigned char* lds) {
;     ...
;         {
;             f32x4 o[2] = {{0, 0, 0, 0}, {0, 0, 0, 0}};
; #pragma unroll
;             for (int kk = 0; kk < 2; ++kk)
; #pragma unroll
;                 for (int c2 = 0; c2 < 2; ++c2) {
;                     const LAS unsigned char* vp = Vc + ((32 * kk + 8 * fq + qq) * VP + 16 * (ct0 + c2) + 4 * pp) * 2;
;                     o[c2] = MFMA16(cat8(tr4(vp), tr4(vp + 4 * VP * 2)), ca[kk], o[c2]);
;                 }
; #pragma unroll
;             for (int kk = 0; kk < 8; ++kk)
; #pragma unroll
;                 for (int c2 = 0; c2 < 2; ++c2) {
;                     const bf16x8 bfr = *(const LAS bf16x8*)(Sp + ((16 * (ct0 + c2) + fr) * GP + 32 * kk + 8 * fq) * 2);
;                     o[c2] = MFMA16(bfr, cq[kk], o[c2]);
;                 }
;             const int t0 = b * SEQ + c * 64;
; #pragma unroll
;             for (int c2 = 0; c2 < 2; ++c2)
;                 *(f32x4*)(ORAW + (size_t)(t0 + 16 * rt + fr) * 2048 + h * 512 + dvs * 64 + 16 * (ct0 + c2) + 4 * fq) = o[c2];
;         }
;         {
; #pragma unroll
;             for (int r2 = 0; r2 < 2; ++r2)
; #pragma unroll
;                 for (int ct = 0; ct < 4; ++ct) S[r2][ct] = S[r2][ct] * cd[r2];
; #pragma unroll
;             for (int kk = 0; kk < 2; ++kk)
; #pragma unroll
;                 for (int ct = 0; ct < 4; ++ct) {
;                     const LAS unsigned char* vp = Vc + ((32 * kk + 8 * fq + qq) * VP + 16 * ct + 4 * pp) * 2;
;                     const bf16x8 bfr = cat8(tr4(vp), tr4(vp + 4 * VP * 2));
; #pragma unroll
;                     for (int r2 = 0; r2 < 2; ++r2) S[r2][ct] = MFMA16(ck[r2][kk], bfr, S[r2][ct]);
;                 }
;         }
;         LAS unsigned char* Sn = Sb + pb * SBB;
; #pragma unroll
;         for (int r2 = 0; r2 < 2; ++r2)
; #pragma unroll
;             for (int ct = 0; ct < 4; ++ct) {
;                 u32x2 w; w.x = pk2(S[r2][ct][0], S[r2][ct][1]); w.y = pk2(S[r2][ct][2], S[r2][ct][3]);
;                 *(LAS u32x2*)(Sn + ((16 * ct + fr) * GP + 16 * (2 * wid + r2) + 4 * fq) * 2) = w;
;             }
; __device__ __forceinline__ void grid_barrier(unsigned* bar, unsigned& gen, unsigned G) {
;     asm volatile("s_waitcnt vmcnt(0) lgkmcnt(0)" ::: "memory");
;     __syncthreads();
;     ++gen;
;     if (threadIdx.x == 0) {
	v_mfma_f32_16x16x32_bf16 v[36:39], v[40:43], v[64:67], v[36:39]
	ds_read_b128 v[40:43], v88 offset:18816
	v_or_b32_e32 v64, s3, v153
	v_ashrrev_i32_e32 v65, 31, v64
	v_mfma_f32_16x16x32_bf16 v[32:35], v[52:55], v[76:79], v[32:35]
	ds_read_b128 v[52:55], v84 offset:18816
	s_waitcnt lgkmcnt(2)
	v_mfma_f32_16x16x32_bf16 v[36:39], v[56:59], v[76:79], v[36:39]
	ds_read_b128 v[56:59], v88 offset:18880
	ds_read_b128 v[60:63], v84 offset:18880
	s_waitcnt lgkmcnt(3)
	v_mfma_f32_16x16x32_bf16 v[32:35], v[40:43], v[68:71], v[32:35]
	v_lshlrev_b64 v[40:41], 13, v[64:65]
	v_lshl_add_u64 v[40:41], v[164:165], 0, v[40:41]
	v_lshl_add_u64 v[40:41], v[40:41], 0, s[6:7]
	s_waitcnt lgkmcnt(2)
	v_mfma_f32_16x16x32_bf16 v[36:39], v[52:55], v[68:71], v[36:39]
	v_lshl_add_u64 v[42:43], v[40:41], 0, s[12:13]
	v_lshl_add_u64 v[40:41], v[40:41], 0, s[14:15]
	s_waitcnt lgkmcnt(1)
	v_mfma_f32_16x16x32_bf16 v[32:35], v[56:59], v[92:95], v[32:35]
	s_nop 7
	global_store_dwordx4 v[42:43], v[32:35], off
	s_waitcnt lgkmcnt(0)
	s_nop 0
	v_mfma_f32_16x16x32_bf16 v[32:35], v[60:63], v[92:95], v[36:39]
	s_nop 7
	global_store_dwordx4 v[40:41], v[32:35], off
	ds_read_b64_tr_b16 v[34:35], v183 offset:9792
	ds_read_b64_tr_b16 v[32:33], v183 offset:9216
	ds_read_b64_tr_b16 v[36:37], v183 offset:9248
	ds_read_b64_tr_b16 v[40:41], v183 offset:9280
	ds_read_b64_tr_b16 v[52:53], v183 offset:9312
	ds_read_b64_tr_b16 v[38:39], v183 offset:9824
	ds_read_b64_tr_b16 v[42:43], v183 offset:9856
	ds_read_b64_tr_b16 v[54:55], v183 offset:9888
	s_waitcnt lgkmcnt(6)
	v_mfma_f32_16x16x32_bf16 v[28:31], v[148:151], v[32:35], v[28:31]
	v_mfma_f32_16x16x32_bf16 v[12:15], v[140:143], v[32:35], v[12:15]
	ds_read_b64_tr_b16 v[34:35], v183 offset:14400
	s_waitcnt lgkmcnt(3)
	v_mfma_f32_16x16x32_bf16 v[24:27], v[148:151], v[36:39], v[24:27]
	v_mfma_f32_16x16x32_bf16 v[8:11], v[140:143], v[36:39], v[8:11]
	ds_read_b64_tr_b16 v[32:33], v183 offset:13824
	ds_read_b64_tr_b16 v[36:37], v183 offset:13856
	ds_read_b64_tr_b16 v[56:57], v183 offset:13888
	ds_read_b64_tr_b16 v[60:61], v183 offset:13920
	ds_read_b64_tr_b16 v[38:39], v183 offset:14432
	ds_read_b64_tr_b16 v[58:59], v183 offset:14464
	ds_read_b64_tr_b16 v[62:63], v183 offset:14496
	s_waitcnt lgkmcnt(9)
	v_mfma_f32_16x16x32_bf16 v[20:23], v[148:151], v[40:43], v[20:23]
	s_waitcnt lgkmcnt(8)
	v_mfma_f32_16x16x32_bf16 v[16:19], v[148:151], v[52:55], v[16:19]
	v_mfma_f32_16x16x32_bf16 v[4:7], v[140:143], v[40:43], v[4:7]
	v_mfma_f32_16x16x32_bf16 v[0:3], v[140:143], v[52:55], v[0:3]
	s_waitcnt lgkmcnt(6)
	v_mfma_f32_16x16x32_bf16 v[28:31], v[144:147], v[32:35], v[28:31]
	s_waitcnt lgkmcnt(2)
	v_mfma_f32_16x16x32_bf16 v[24:27], v[144:147], v[36:39], v[24:27]
	s_waitcnt lgkmcnt(1)
	v_mfma_f32_16x16x32_bf16 v[20:23], v[144:147], v[56:59], v[20:23]
	s_nop 3
	v_cvt_pk_bf16_f32 v28, v28, v29
	v_cvt_pk_bf16_f32 v29, v30, v31
	v_add_u32_e32 v30, 0, v182
	s_waitcnt lgkmcnt(0)
	v_mfma_f32_16x16x32_bf16 v[16:19], v[144:147], v[60:63], v[16:19]
	v_cvt_pk_bf16_f32 v24, v24, v25
	v_cvt_pk_bf16_f32 v25, v26, v27
	v_add_u32_e32 v26, 0, v181
	v_mfma_f32_16x16x32_bf16 v[12:15], v[44:47], v[32:35], v[12:15]
	v_cvt_pk_bf16_f32 v20, v20, v21
	v_cvt_pk_bf16_f32 v21, v22, v23
	v_add_u32_e32 v22, 0, v180
	v_mfma_f32_16x16x32_bf16 v[8:11], v[44:47], v[36:39], v[8:11]
	v_cvt_pk_bf16_f32 v16, v16, v17
	v_cvt_pk_bf16_f32 v17, v18, v19
	v_add_u32_e32 v18, 0, v179
	v_mfma_f32_16x16x32_bf16 v[4:7], v[44:47], v[56:59], v[4:7]
	v_cvt_pk_bf16_f32 v12, v12, v13
	v_cvt_pk_bf16_f32 v13, v14, v15
	v_add_u32_e32 v14, 0, v178
	v_mfma_f32_16x16x32_bf16 v[0:3], v[44:47], v[60:63], v[0:3]
	v_cvt_pk_bf16_f32 v8, v8, v9
	v_cvt_pk_bf16_f32 v9, v10, v11
	v_add_u32_e32 v10, 0, v163
	s_nop 0
	v_cvt_pk_bf16_f32 v4, v4, v5
	v_cvt_pk_bf16_f32 v5, v6, v7
	v_add_u32_e32 v6, 0, v159
	s_nop 0
	v_cvt_pk_bf16_f32 v0, v0, v1
	v_cvt_pk_bf16_f32 v1, v2, v3
	v_add_u32_e32 v2, 0, v155
	ds_write_b64 v30, v[28:29] offset:52224
	ds_write_b64 v26, v[24:25] offset:52224
	ds_write_b64 v22, v[20:21] offset:52224
	ds_write_b64 v18, v[16:17] offset:52224
	ds_write_b64 v14, v[12:13] offset:52224
	ds_write_b64 v10, v[8:9] offset:52224
	ds_write_b64 v6, v[4:5] offset:52224
	ds_write_b64 v2, v[0:1] offset:52224
	s_waitcnt lgkmcnt(0)
	s_barrier
.LBB0_361:
	s_setprio 0
	s_mov_b64 s[12:13], s[0:1]
	s_waitcnt vmcnt(0) lgkmcnt(0)
	s_waitcnt lgkmcnt(0)
	s_barrier
	s_and_saveexec_b64 s[10:11], s[4:5]
	s_cbranch_execz .LBB0_384
	s_load_dwordx2 s[12:13], s[12:13], 0xb8
	buffer_wbl2 sc1
	s_waitcnt vmcnt(0) lgkmcnt(0)
	s_waitcnt vmcnt(0)
	s_add_u32 s14, s12, 0x80000
	s_addc_u32 s15, s13, 0
	s_and_b32 s3, s40, 7
	s_cmp_lg_u32 s3, 0
	s_cbranch_scc0 .LBB0_368
	s_mov_b64 s[18:19], exec
	v_mbcnt_lo_u32_b32 v0, s18, 0
	v_mbcnt_hi_u32_b32 v0, s19, v0
	v_cmp_eq_u32_e32 vcc, 0, v0
	s_and_saveexec_b64 s[16:17], vcc
	s_cbranch_execz .LBB0_365
	s_bcnt1_i32_b64 s3, s[18:19]
	v_mov_b32_e32 v0, 0
	v_mov_b32_e32 v1, s3
	global_atomic_add v0, v1, s[14:15]
